# v44 + top-of-chunk xl loads with scalar-base addressing
# baseline (speedup 1.0000x reference)
.LBB0_336:
	v_readlane_b32 s98, v254, 52
	v_readlane_b32 s99, v254, 53
	v_readfirstlane_b32 s100, v158
	s_nop 3
	v_subrev_u32_e32 v2, s98, v176
	s_add_i32 s100, s100, s13
	s_lshl_b32 s100, s100, 13
	s_add_u32 s98, s98, s100
	s_addc_u32 s99, s99, 0
	s_add_u32 s98, s98, 0x1c000
	s_addc_u32 s99, s99, 0
	global_load_dword v108, v2, s[98:99]
	s_add_u32 s98, s98, 0x2000
	s_addc_u32 s99, s99, 0
	global_load_dword v107, v2, s[98:99]
	s_add_u32 s98, s98, 0x2000
	s_addc_u32 s99, s99, 0
	global_load_dword v106, v2, s[98:99]
	s_add_u32 s98, s98, 0x2000
	s_addc_u32 s99, s99, 0
	global_load_dword v105, v2, s[98:99]
	s_add_u32 s98, s98, 0x2000
	s_addc_u32 s99, s99, 0
	global_load_dword v104, v2, s[98:99]
	s_add_u32 s98, s98, 0x2000
	s_addc_u32 s99, s99, 0
	global_load_dword v103, v2, s[98:99]
	s_add_u32 s98, s98, 0x2000
	s_addc_u32 s99, s99, 0
	global_load_dword v102, v2, s[98:99]
	s_add_u32 s98, s98, 0x2000
	s_addc_u32 s99, s99, 0
	global_load_dword v101, v2, s[98:99]
	s_add_u32 s98, s98, 0x2000
	s_addc_u32 s99, s99, 0
	global_load_dword v100, v2, s[98:99]
	s_add_u32 s98, s98, 0x2000
	s_addc_u32 s99, s99, 0
	global_load_dword v99, v2, s[98:99]
	s_add_u32 s98, s98, 0x2000
	s_addc_u32 s99, s99, 0
	global_load_dword v98, v2, s[98:99]
	s_add_u32 s98, s98, 0x2000
	s_addc_u32 s99, s99, 0
	global_load_dword v97, v2, s[98:99]
	s_add_u32 s98, s98, 0x2000
	s_addc_u32 s99, s99, 0
	global_load_dword v96, v2, s[98:99]
	s_add_u32 s98, s98, 0x2000
	s_addc_u32 s99, s99, 0
	global_load_dword v95, v2, s[98:99]
	s_add_u32 s98, s98, 0x2000
	s_addc_u32 s99, s99, 0
	global_load_dword v94, v2, s[98:99]
	s_add_u32 s98, s98, 0x2000
	s_addc_u32 s99, s99, 0
	global_load_dword v3, v2, s[98:99]
	s_add_u32 s98, s98, 0x2000
	s_addc_u32 s99, s99, 0
	global_load_dword v69, v2, s[98:99]
	s_add_u32 s98, s98, 0x2000
	s_addc_u32 s99, s99, 0
	global_load_dword v71, v2, s[98:99]
	s_andn2_b64 vcc, exec, s[92:93]
	s_cbranch_vccnz .LBB0_340
	s_waitcnt vmcnt(18)
	v_add_f32_e32 v2, v203, v153
	s_mov_b32 s14, 0x41a00000
	v_cmp_nlt_f32_e32 vcc, s14, v2
	s_and_saveexec_b64 s[94:95], vcc
	s_cbranch_execz .LBB0_339
	v_mul_f32_e32 v2, 0x3fb8aa3b, v2
	v_exp_f32_e32 v2, v2
	s_mov_b32 s14, 0x3f2aaaab
	v_add_f32_e32 v68, 1.0, v2
	v_frexp_mant_f32_e32 v74, v68
	v_cvt_f64_f32_e32 v[72:73], v68
	v_add_f32_e32 v70, -1.0, v68
	v_frexp_exp_i32_f64_e32 v72, v[72:73]
	v_cmp_gt_f32_e32 vcc, s14, v74
	v_sub_f32_e32 v75, v70, v68
	v_sub_f32_e32 v70, v2, v70
	v_subbrev_co_u32_e32 v80, vcc, 0, v72, vcc
	v_add_f32_e32 v75, 1.0, v75
	v_sub_u32_e32 v72, 0, v80
	v_add_f32_e32 v70, v70, v75
	v_ldexp_f32 v68, v68, v72
	v_ldexp_f32 v70, v70, v72
	v_add_f32_e32 v72, -1.0, v68
	v_add_f32_e32 v73, 1.0, v72
	v_sub_f32_e32 v73, v68, v73
	v_add_f32_e32 v74, v70, v73
	v_add_f32_e32 v73, 1.0, v68
	v_add_f32_e32 v75, -1.0, v73
	v_sub_f32_e32 v68, v68, v75
	v_add_f32_e32 v68, v70, v68
	v_add_f32_e32 v70, v73, v68
	v_rcp_f32_e32 v81, v70
	v_sub_f32_e32 v73, v70, v73
	v_sub_f32_e32 v68, v68, v73
	v_add_f32_e32 v73, v72, v74
	v_sub_f32_e32 v72, v73, v72
	v_mul_f32_e32 v83, v73, v81
	v_sub_f32_e32 v82, v74, v72
	v_mul_f32_e32 v74, v70, v83
	v_fma_f32 v76, v83, v70, -v74
	v_fmac_f32_e32 v76, v83, v68
	v_add_f32_e32 v72, v74, v76
	v_sub_f32_e32 v75, v73, v72
	v_pk_add_f32 v[78:79], v[72:73], v[74:75] neg_lo:[0,1] neg_hi:[0,1]
	v_mov_b32_e32 v77, v72
	v_pk_add_f32 v[72:73], v[78:79], v[76:77] neg_lo:[0,1] neg_hi:[0,1]
	s_mov_b32 s14, 0x3f317218
	v_add_f32_e32 v73, v82, v73
	v_add_f32_e32 v72, v72, v73
	v_add_f32_e32 v73, v75, v72
	v_mul_f32_e32 v82, v81, v73
	v_mul_f32_e32 v74, v70, v82
	v_fma_f32 v76, v82, v70, -v74
	v_fmac_f32_e32 v76, v82, v68
	v_sub_f32_e32 v68, v75, v73
	v_add_f32_e32 v68, v72, v68
	v_add_f32_e32 v72, v74, v76
	v_sub_f32_e32 v75, v73, v72
	v_pk_add_f32 v[78:79], v[72:73], v[74:75] neg_lo:[0,1] neg_hi:[0,1]
	v_mov_b32_e32 v77, v72
	v_pk_add_f32 v[72:73], v[78:79], v[76:77] neg_lo:[0,1] neg_hi:[0,1]
	v_add_f32_e32 v70, v83, v82
	v_add_f32_e32 v68, v68, v73
	v_add_f32_e32 v68, v72, v68
	v_add_f32_e32 v68, v75, v68
	v_sub_f32_e32 v72, v70, v83
	v_mul_f32_e32 v68, v81, v68
	v_sub_f32_e32 v72, v82, v72
	v_add_f32_e32 v68, v72, v68
	v_add_f32_e32 v73, v70, v68
	v_mul_f32_e32 v74, v73, v73
	v_fmamk_f32 v72, v74, 0x3e9b6dac, v193
	v_fmaak_f32 v153, v74, v72, 0x3f2aaada
	v_cvt_f32_i32_e32 v72, v80
	v_sub_f32_e32 v70, v73, v70
	v_ldexp_f32 v75, v73, 1
	v_mul_f32_e32 v73, v73, v74
	v_pk_mul_f32 v[76:77], v[72:73], v[152:153]
	v_sub_f32_e32 v68, v68, v70
	v_fma_f32 v74, v72, s14, -v76
	v_fmac_f32_e32 v74, 0xb102e308, v72
	v_pk_add_f32 v[72:73], v[76:77], v[74:75]
	v_ldexp_f32 v68, v68, 1
	v_sub_f32_e32 v70, v73, v75
	v_sub_f32_e32 v70, v77, v70
	v_add_f32_e32 v79, v68, v70
	v_mov_b32_e32 v78, v76
	v_pk_add_f32 v[76:77], v[72:73], v[76:77] neg_lo:[0,1] neg_hi:[0,1]
	v_pk_add_f32 v[80:81], v[72:73], v[78:79]
	v_mov_b32_e32 v75, v72
	v_mov_b32_e32 v77, v81
	v_pk_add_f32 v[82:83], v[74:75], v[76:77] neg_lo:[0,1] neg_hi:[0,1]
	v_pk_add_f32 v[74:75], v[74:75], v[76:77]
	v_mov_b32_e32 v78, v79
	v_pk_add_f32 v[76:77], v[74:75], v[72:73] op_sel:[1,0] op_sel_hi:[0,1] neg_lo:[0,1] neg_hi:[0,1]
	v_pk_add_f32 v[84:85], v[80:81], v[76:77] op_sel_hi:[1,0] neg_lo:[0,1] neg_hi:[0,1]
	v_mov_b32_e32 v80, v81
	v_mov_b32_e32 v81, v75
	v_pk_mov_b32 v[76:77], v[72:73], v[76:77] op_sel:[1,0]
	v_mov_b32_e32 v79, v72
	v_pk_add_f32 v[76:77], v[80:81], v[76:77] neg_lo:[0,1] neg_hi:[0,1]
	v_mov_b32_e32 v84, v82
	v_pk_add_f32 v[72:73], v[78:79], v[76:77] neg_lo:[0,1] neg_hi:[0,1]
	v_mov_b32_e32 v83, v75
	v_pk_add_f32 v[76:77], v[84:85], v[72:73]
	s_mov_b32 s14, 0x7f800000
	v_pk_add_f32 v[78:79], v[76:77], v[76:77] op_sel:[0,1] op_sel_hi:[1,0]
	v_cmp_neq_f32_e32 vcc, s14, v2
	v_pk_add_f32 v[74:75], v[74:75], v[78:79] op_sel:[1,0] op_sel_hi:[0,1]
	v_mov_b32_e32 v77, v74
	v_pk_add_f32 v[80:81], v[76:77], v[82:83] neg_lo:[0,1] neg_hi:[0,1]
	v_mov_b32_e32 v73, v78
	v_sub_f32_e32 v68, v76, v80
	v_pk_add_f32 v[72:73], v[72:73], v[80:81] neg_lo:[0,1] neg_hi:[0,1]
	v_sub_f32_e32 v68, v82, v68
	v_add_f32_e32 v68, v72, v68
	v_add_f32_e32 v68, v68, v73
	v_add_f32_e32 v68, v74, v68
	v_cndmask_b32_e32 v68, v196, v68, vcc
	v_cmp_ngt_f32_e32 vcc, -1.0, v2
	s_mov_b32 s14, 0x33800000
	s_nop 0
	v_cndmask_b32_e32 v68, v197, v68, vcc
	v_cmp_neq_f32_e32 vcc, -1.0, v2
	s_nop 1
	v_cndmask_b32_e32 v68, v198, v68, vcc
	v_cmp_lt_f32_e64 vcc, |v2|, s14
	s_nop 1
	v_cndmask_b32_e32 v2, v68, v2, vcc
